# also balanced LDS-DMA staging (4+4 per segment, extra vmcnt(4)) in the layer-1 (final) down-GEMM K-loop
# baseline (speedup 1.0000x reference)
.LBB0_2062:
	s_mov_b64 s[22:23], s[12:13]
	s_add_u32 s56, s22, 0x100
	s_addc_u32 s57, s23, 0
	s_add_i32 s54, s55, 1
	s_lshl_b32 s12, s54, 5
	s_add_i32 s12, s12, s30
	s_cmp_lt_i32 s12, 32
	s_cselect_b64 s[20:21], -1, 0
	s_cmp_gt_i32 s12, 31
	s_mov_b32 s16, s53
	s_cselect_b64 s[14:15], -1, 0
	s_ashr_i32 s53, s12, 2
	s_and_b64 s[12:13], s[20:21], exec
	s_cselect_b32 s12, s53, s16
	s_cselect_b32 s16, s34, s34
	s_ashr_i32 s17, s16, 31
	s_lshl_b64 s[16:17], s[16:17], 22
	s_add_u32 s16, s31, s16
	s_addc_u32 s17, s35, s17
	s_and_b64 s[24:25], s[20:21], exec
	s_cselect_b32 s58, s17, s19
	s_cselect_b32 s59, s16, s18
	s_ashr_i32 s13, s12, 31
	s_lshl_b64 s[12:13], s[12:13], 22
	s_add_u32 s12, s36, s12
	s_addc_u32 s13, s37, s13
	s_and_b64 s[24:25], s[20:21], exec
	s_cselect_b32 s60, s13, s23
	s_cselect_b32 s61, s12, s22
	v_lshl_add_u64 v[140:141], s[18:19], 0, v[136:137]
	v_lshl_add_u64 v[142:143], s[18:19], 0, v[138:139]
	s_lshr_b32 s84, s88, 2
	s_mul_i32 s85, s84, 0x3000
	s_add_i32 s85, s85, s1
	s_mul_i32 s96, s84, 0x180000
	s_mov_b32 s97, 0
	s_sub_u32 s86, s96, 0x200000
	s_subb_u32 s87, 0, 0
	s_mov_b32 s62, -2
	s_mov_b64 s[22:23], 0
.LBB0_2063:
	v_add_u32_e32 v147, s33, v145
	ds_read_b128 v[148:151], v147
	ds_read_b128 v[152:155], v147 offset:1024
	ds_read_b128 v[156:159], v147 offset:2048
	ds_read_b128 v[160:163], v147 offset:3072
	v_add_u32_e32 v147, s45, v145
	s_add_u32 s24, s18, s22
	ds_read_b128 v[164:167], v147
	ds_read_b128 v[168:171], v147 offset:1024
	ds_read_b128 v[172:175], v147 offset:2048
	ds_read_b128 v[176:179], v147 offset:3072
	s_addc_u32 s25, s19, s23
	s_add_u32 s24, s24, 0x100
	s_addc_u32 s25, s25, 0
	s_add_u32 s63, s56, s22
	s_addc_u32 s64, s57, s23
	s_cmpk_eq_i32 s22, 0x3f00
	s_cselect_b32 s27, s58, s25
	s_cselect_b32 s26, s59, s24
	s_cselect_b32 s25, s60, s64
	s_cselect_b32 s24, s61, s63
	s_add_u32 s98, s22, s86
	s_addc_u32 s99, s23, s87
	s_add_i32 m0, s85, 0x8000
	v_lshl_add_u64 v[214:215], v[140:141], 0, s[98:99]
	ds_read_b128 v[180:183], v146
	ds_read_b128 v[184:187], v146 offset:1024
	ds_read_b128 v[188:191], v146 offset:2048
	ds_read_b128 v[192:195], v146 offset:3072
	ds_read_b128 v[196:199], v146 offset:4096
	ds_read_b128 v[202:205], v146 offset:5120
	ds_read_b128 v[206:209], v146 offset:6144
	ds_read_b128 v[210:213], v146 offset:7168
	global_load_lds_dwordx4 v[214:215], off
	s_add_u32 s98, s98, 0x80000
	s_addc_u32 s99, s99, 0
	s_add_i32 m0, s85, 0x9000
	v_lshl_add_u64 v[214:215], v[140:141], 0, s[98:99]
	global_load_lds_dwordx4 v[214:215], off
	s_add_u32 s98, s98, 0x80000
	s_addc_u32 s99, s99, 0
	s_add_i32 m0, s85, 0xa000
	v_lshl_add_u64 v[214:215], v[140:141], 0, s[98:99]
	global_load_lds_dwordx4 v[214:215], off
	s_add_u32 s98, s98, 0x80000
	s_addc_u32 s99, s99, 0
	s_add_i32 m0, s85, 0xb000
	v_lshl_add_u64 v[214:215], v[140:141], 0, s[98:99]
	global_load_lds_dwordx4 v[214:215], off
	s_waitcnt vmcnt(8)
	s_waitcnt lgkmcnt(0)
	s_barrier
	s_setprio 1
	s_waitcnt lgkmcnt(0)
	v_mfma_f32_16x16x32_bf16 v[124:127], v[148:151], v[180:183], v[124:127]
	v_mfma_f32_16x16x32_bf16 v[120:123], v[156:159], v[180:183], v[120:123]
	v_mfma_f32_16x16x32_bf16 v[108:111], v[148:151], v[188:191], v[108:111]
	v_mfma_f32_16x16x32_bf16 v[104:107], v[156:159], v[188:191], v[104:107]
	v_mfma_f32_16x16x32_bf16 v[92:95], v[148:151], v[196:199], v[92:95]
	v_mfma_f32_16x16x32_bf16 v[88:91], v[156:159], v[196:199], v[88:91]
	v_mfma_f32_16x16x32_bf16 v[76:79], v[148:151], v[206:209], v[76:79]
	v_mfma_f32_16x16x32_bf16 v[72:75], v[156:159], v[206:209], v[72:75]
	v_mfma_f32_16x16x32_bf16 v[124:127], v[152:155], v[184:187], v[124:127]
	v_mfma_f32_16x16x32_bf16 v[120:123], v[160:163], v[184:187], v[120:123]
	v_mfma_f32_16x16x32_bf16 v[108:111], v[152:155], v[192:195], v[108:111]
	v_mfma_f32_16x16x32_bf16 v[104:107], v[160:163], v[192:195], v[104:107]
	v_mfma_f32_16x16x32_bf16 v[92:95], v[152:155], v[202:205], v[92:95]
	v_mfma_f32_16x16x32_bf16 v[88:91], v[160:163], v[202:205], v[88:91]
	v_mfma_f32_16x16x32_bf16 v[76:79], v[152:155], v[210:213], v[76:79]
	v_mfma_f32_16x16x32_bf16 v[72:75], v[160:163], v[210:213], v[72:75]
	s_setprio 0
	s_setprio 1
	v_mfma_f32_16x16x32_bf16 v[116:119], v[164:167], v[180:183], v[116:119]
	v_mfma_f32_16x16x32_bf16 v[112:115], v[172:175], v[180:183], v[112:115]
	v_mfma_f32_16x16x32_bf16 v[100:103], v[164:167], v[188:191], v[100:103]
	v_mfma_f32_16x16x32_bf16 v[96:99], v[172:175], v[188:191], v[96:99]
	v_mfma_f32_16x16x32_bf16 v[84:87], v[164:167], v[196:199], v[84:87]
	v_mfma_f32_16x16x32_bf16 v[80:83], v[172:175], v[196:199], v[80:83]
	v_mfma_f32_16x16x32_bf16 v[68:71], v[164:167], v[206:209], v[68:71]
	v_mfma_f32_16x16x32_bf16 v[64:67], v[172:175], v[206:209], v[64:67]
	v_mfma_f32_16x16x32_bf16 v[116:119], v[168:171], v[184:187], v[116:119]
	v_mfma_f32_16x16x32_bf16 v[112:115], v[176:179], v[184:187], v[112:115]
	v_mfma_f32_16x16x32_bf16 v[100:103], v[168:171], v[192:195], v[100:103]
	v_mfma_f32_16x16x32_bf16 v[96:99], v[176:179], v[192:195], v[96:99]
	v_mfma_f32_16x16x32_bf16 v[84:87], v[168:171], v[202:205], v[84:87]
	v_mfma_f32_16x16x32_bf16 v[80:83], v[176:179], v[202:205], v[80:83]
	v_mfma_f32_16x16x32_bf16 v[68:71], v[168:171], v[210:213], v[68:71]
	v_mfma_f32_16x16x32_bf16 v[64:67], v[176:179], v[210:213], v[64:67]
	s_setprio 0
	s_barrier
	s_mov_b32 m0, s48
	v_lshl_add_u64 v[214:215], s[24:25], 0, v[132:133]
	s_add_u32 s64, s24, 0x200000
	ds_read_b128 v[180:183], v146 offset:16384
	ds_read_b128 v[184:187], v146 offset:17408
	ds_read_b128 v[188:191], v146 offset:18432
	ds_read_b128 v[192:195], v146 offset:19456
	ds_read_b128 v[196:199], v146 offset:20480
	ds_read_b128 v[202:205], v146 offset:21504
	ds_read_b128 v[206:209], v146 offset:22528
	ds_read_b128 v[210:213], v146 offset:23552
	global_load_lds_dwordx4 v[214:215], off
	v_lshl_add_u64 v[216:217], s[24:25], 0, v[128:129]
	s_mov_b32 m0, s49
	s_addc_u32 s65, s25, 0
	global_load_lds_dwordx4 v[216:217], off
	v_lshl_add_u64 v[218:219], s[64:65], 0, v[132:133]
	s_mov_b32 m0, s50
	global_load_lds_dwordx4 v[218:219], off
	v_lshl_add_u64 v[218:219], s[64:65], 0, v[128:129]
	s_mov_b32 m0, s51
	s_nop 0
	global_load_lds_dwordx4 v[218:219], off
	s_waitcnt vmcnt(8)
	s_waitcnt lgkmcnt(0)
	s_barrier
	s_setprio 1
	s_waitcnt lgkmcnt(0)
	v_mfma_f32_16x16x32_bf16 v[60:63], v[148:151], v[180:183], v[60:63]
	v_mfma_f32_16x16x32_bf16 v[56:59], v[156:159], v[180:183], v[56:59]
	v_mfma_f32_16x16x32_bf16 v[44:47], v[148:151], v[188:191], v[44:47]
	v_mfma_f32_16x16x32_bf16 v[40:43], v[156:159], v[188:191], v[40:43]
	v_mfma_f32_16x16x32_bf16 v[28:31], v[148:151], v[196:199], v[28:31]
	v_mfma_f32_16x16x32_bf16 v[24:27], v[156:159], v[196:199], v[24:27]
	v_mfma_f32_16x16x32_bf16 v[12:15], v[148:151], v[206:209], v[12:15]
	v_mfma_f32_16x16x32_bf16 v[8:11], v[156:159], v[206:209], v[8:11]
	v_mfma_f32_16x16x32_bf16 v[60:63], v[152:155], v[184:187], v[60:63]
	v_mfma_f32_16x16x32_bf16 v[56:59], v[160:163], v[184:187], v[56:59]
	v_mfma_f32_16x16x32_bf16 v[44:47], v[152:155], v[192:195], v[44:47]
	v_mfma_f32_16x16x32_bf16 v[40:43], v[160:163], v[192:195], v[40:43]
	v_mfma_f32_16x16x32_bf16 v[28:31], v[152:155], v[202:205], v[28:31]
	v_mfma_f32_16x16x32_bf16 v[24:27], v[160:163], v[202:205], v[24:27]
	v_mfma_f32_16x16x32_bf16 v[12:15], v[152:155], v[210:213], v[12:15]
	v_mfma_f32_16x16x32_bf16 v[8:11], v[160:163], v[210:213], v[8:11]
	s_setprio 0
	s_setprio 1
	v_mfma_f32_16x16x32_bf16 v[52:55], v[164:167], v[180:183], v[52:55]
	v_mfma_f32_16x16x32_bf16 v[48:51], v[172:175], v[180:183], v[48:51]
	v_mfma_f32_16x16x32_bf16 v[36:39], v[164:167], v[188:191], v[36:39]
	v_mfma_f32_16x16x32_bf16 v[32:35], v[172:175], v[188:191], v[32:35]
	v_mfma_f32_16x16x32_bf16 v[20:23], v[164:167], v[196:199], v[20:23]
	v_mfma_f32_16x16x32_bf16 v[16:19], v[172:175], v[196:199], v[16:19]
	v_mfma_f32_16x16x32_bf16 v[4:7], v[164:167], v[206:209], v[4:7]
	v_mfma_f32_16x16x32_bf16 v[0:3], v[172:175], v[206:209], v[0:3]
	v_mfma_f32_16x16x32_bf16 v[52:55], v[168:171], v[184:187], v[52:55]
	v_mfma_f32_16x16x32_bf16 v[48:51], v[176:179], v[184:187], v[48:51]
	v_mfma_f32_16x16x32_bf16 v[36:39], v[168:171], v[192:195], v[36:39]
	v_mfma_f32_16x16x32_bf16 v[32:35], v[176:179], v[192:195], v[32:35]
	v_mfma_f32_16x16x32_bf16 v[20:23], v[168:171], v[202:205], v[20:23]
	v_mfma_f32_16x16x32_bf16 v[16:19], v[176:179], v[202:205], v[16:19]
	v_mfma_f32_16x16x32_bf16 v[4:7], v[168:171], v[210:213], v[4:7]
	v_mfma_f32_16x16x32_bf16 v[0:3], v[176:179], v[210:213], v[0:3]
	s_setprio 0
	s_waitcnt vmcnt(4)
	s_barrier
	v_add_u32_e32 v147, s52, v145
	s_add_i32 s63, 0, 0x1c000
	ds_read_b128 v[148:151], v147
	ds_read_b128 v[152:155], v147 offset:1024
	ds_read_b128 v[156:159], v147 offset:2048
	ds_read_b128 v[160:163], v147 offset:3072
	v_add_u32_e32 v147, s63, v145
	ds_read_b128 v[164:167], v147
	ds_read_b128 v[168:171], v147 offset:1024
	ds_read_b128 v[172:175], v147 offset:2048
	ds_read_b128 v[176:179], v147 offset:3072
	s_add_u32 s98, s26, s96
	s_addc_u32 s99, s27, s97
	s_add_i32 m0, s85, 0
	v_lshl_add_u64 v[222:223], s[98:99], 0, v[134:135]
	ds_read_b128 v[180:183], v146 offset:32768
	ds_read_b128 v[184:187], v146 offset:33792
	ds_read_b128 v[188:191], v146 offset:34816
	ds_read_b128 v[192:195], v146 offset:35840
	ds_read_b128 v[196:199], v146 offset:36864
	ds_read_b128 v[202:205], v146 offset:37888
	ds_read_b128 v[206:209], v146 offset:38912
	ds_read_b128 v[210:213], v146 offset:39936
	global_load_lds_dwordx4 v[222:223], off
	s_add_u32 s98, s98, 0x80000
	s_addc_u32 s99, s99, 0
	s_add_i32 m0, s85, 0x1000
	v_lshl_add_u64 v[222:223], s[98:99], 0, v[134:135]
	global_load_lds_dwordx4 v[222:223], off
	s_add_u32 s98, s98, 0x80000
	s_addc_u32 s99, s99, 0
	s_add_i32 m0, s85, 0x2000
	v_lshl_add_u64 v[222:223], s[98:99], 0, v[134:135]
	global_load_lds_dwordx4 v[222:223], off
	s_add_u32 s98, s98, 0x80000
	s_addc_u32 s99, s99, 0
	s_add_i32 m0, s85, 0x3000
	v_lshl_add_u64 v[222:223], s[98:99], 0, v[134:135]
	global_load_lds_dwordx4 v[222:223], off
	s_waitcnt vmcnt(8)
	s_waitcnt lgkmcnt(0)
	s_barrier
	s_setprio 1
	s_waitcnt lgkmcnt(0)
	v_mfma_f32_16x16x32_bf16 v[124:127], v[148:151], v[180:183], v[124:127]
	v_mfma_f32_16x16x32_bf16 v[120:123], v[156:159], v[180:183], v[120:123]
	v_mfma_f32_16x16x32_bf16 v[108:111], v[148:151], v[188:191], v[108:111]
	v_mfma_f32_16x16x32_bf16 v[104:107], v[156:159], v[188:191], v[104:107]
	v_mfma_f32_16x16x32_bf16 v[92:95], v[148:151], v[196:199], v[92:95]
	v_mfma_f32_16x16x32_bf16 v[88:91], v[156:159], v[196:199], v[88:91]
	v_mfma_f32_16x16x32_bf16 v[76:79], v[148:151], v[206:209], v[76:79]
	v_mfma_f32_16x16x32_bf16 v[72:75], v[156:159], v[206:209], v[72:75]
	v_mfma_f32_16x16x32_bf16 v[124:127], v[152:155], v[184:187], v[124:127]
	v_mfma_f32_16x16x32_bf16 v[120:123], v[160:163], v[184:187], v[120:123]
	v_mfma_f32_16x16x32_bf16 v[108:111], v[152:155], v[192:195], v[108:111]
	v_mfma_f32_16x16x32_bf16 v[104:107], v[160:163], v[192:195], v[104:107]
	v_mfma_f32_16x16x32_bf16 v[92:95], v[152:155], v[202:205], v[92:95]
	v_mfma_f32_16x16x32_bf16 v[88:91], v[160:163], v[202:205], v[88:91]
	v_mfma_f32_16x16x32_bf16 v[76:79], v[152:155], v[210:213], v[76:79]
	v_mfma_f32_16x16x32_bf16 v[72:75], v[160:163], v[210:213], v[72:75]
	s_setprio 0
	s_setprio 1
	v_mfma_f32_16x16x32_bf16 v[116:119], v[164:167], v[180:183], v[116:119]
	v_mfma_f32_16x16x32_bf16 v[112:115], v[172:175], v[180:183], v[112:115]
	v_mfma_f32_16x16x32_bf16 v[100:103], v[164:167], v[188:191], v[100:103]
	v_mfma_f32_16x16x32_bf16 v[96:99], v[172:175], v[188:191], v[96:99]
	v_mfma_f32_16x16x32_bf16 v[84:87], v[164:167], v[196:199], v[84:87]
	v_mfma_f32_16x16x32_bf16 v[80:83], v[172:175], v[196:199], v[80:83]
	v_mfma_f32_16x16x32_bf16 v[68:71], v[164:167], v[206:209], v[68:71]
	v_mfma_f32_16x16x32_bf16 v[64:67], v[172:175], v[206:209], v[64:67]
	v_mfma_f32_16x16x32_bf16 v[116:119], v[168:171], v[184:187], v[116:119]
	v_mfma_f32_16x16x32_bf16 v[112:115], v[176:179], v[184:187], v[112:115]
	v_mfma_f32_16x16x32_bf16 v[100:103], v[168:171], v[192:195], v[100:103]
	v_mfma_f32_16x16x32_bf16 v[96:99], v[176:179], v[192:195], v[96:99]
	v_mfma_f32_16x16x32_bf16 v[84:87], v[168:171], v[202:205], v[84:87]
	v_mfma_f32_16x16x32_bf16 v[80:83], v[176:179], v[202:205], v[80:83]
	v_mfma_f32_16x16x32_bf16 v[68:71], v[168:171], v[210:213], v[68:71]
	v_mfma_f32_16x16x32_bf16 v[64:67], v[176:179], v[210:213], v[64:67]
	s_setprio 0
	s_barrier
	s_add_i32 s26, s52, s38
	v_lshl_add_u64 v[214:215], v[214:215], 0, s[8:9]
	s_mov_b32 m0, s26
	ds_read_b128 v[180:183], v146 offset:49152
	ds_read_b128 v[184:187], v146 offset:50176
	ds_read_b128 v[188:191], v146 offset:51200
	ds_read_b128 v[192:195], v146 offset:52224
	ds_read_b128 v[196:199], v146 offset:53248
	ds_read_b128 v[202:205], v146 offset:54272
	ds_read_b128 v[206:209], v146 offset:55296
	ds_read_b128 v[210:213], v146 offset:56320
	global_load_lds_dwordx4 v[214:215], off
	s_add_i32 m0, s26, 0x2000
	s_add_u32 s24, s24, 0x200080
	v_lshl_add_u64 v[214:215], v[216:217], 0, s[8:9]
	s_addc_u32 s25, s25, 0
	s_add_i32 s26, s63, s38
	global_load_lds_dwordx4 v[214:215], off
	v_lshl_add_u64 v[214:215], s[24:25], 0, v[132:133]
	s_mov_b32 m0, s26
	s_nop 0
	global_load_lds_dwordx4 v[214:215], off
	v_lshl_add_u64 v[214:215], s[24:25], 0, v[128:129]
	s_add_i32 m0, s26, 0x2000
	s_nop 0
	global_load_lds_dwordx4 v[214:215], off
	s_waitcnt vmcnt(8)
	s_waitcnt lgkmcnt(0)
	s_barrier
	s_setprio 1
	s_waitcnt lgkmcnt(0)
	v_mfma_f32_16x16x32_bf16 v[60:63], v[148:151], v[180:183], v[60:63]
	v_mfma_f32_16x16x32_bf16 v[56:59], v[156:159], v[180:183], v[56:59]
	v_mfma_f32_16x16x32_bf16 v[44:47], v[148:151], v[188:191], v[44:47]
	v_mfma_f32_16x16x32_bf16 v[40:43], v[156:159], v[188:191], v[40:43]
	v_mfma_f32_16x16x32_bf16 v[28:31], v[148:151], v[196:199], v[28:31]
	v_mfma_f32_16x16x32_bf16 v[24:27], v[156:159], v[196:199], v[24:27]
	v_mfma_f32_16x16x32_bf16 v[12:15], v[148:151], v[206:209], v[12:15]
	v_mfma_f32_16x16x32_bf16 v[8:11], v[156:159], v[206:209], v[8:11]
	v_mfma_f32_16x16x32_bf16 v[60:63], v[152:155], v[184:187], v[60:63]
	v_mfma_f32_16x16x32_bf16 v[56:59], v[160:163], v[184:187], v[56:59]
	v_mfma_f32_16x16x32_bf16 v[44:47], v[152:155], v[192:195], v[44:47]
	v_mfma_f32_16x16x32_bf16 v[40:43], v[160:163], v[192:195], v[40:43]
	v_mfma_f32_16x16x32_bf16 v[28:31], v[152:155], v[202:205], v[28:31]
	v_mfma_f32_16x16x32_bf16 v[24:27], v[160:163], v[202:205], v[24:27]
	v_mfma_f32_16x16x32_bf16 v[12:15], v[152:155], v[210:213], v[12:15]
	v_mfma_f32_16x16x32_bf16 v[8:11], v[160:163], v[210:213], v[8:11]
	s_setprio 0
	s_setprio 1
	v_mfma_f32_16x16x32_bf16 v[52:55], v[164:167], v[180:183], v[52:55]
	v_mfma_f32_16x16x32_bf16 v[48:51], v[172:175], v[180:183], v[48:51]
	v_mfma_f32_16x16x32_bf16 v[36:39], v[164:167], v[188:191], v[36:39]
	v_mfma_f32_16x16x32_bf16 v[32:35], v[172:175], v[188:191], v[32:35]
	v_mfma_f32_16x16x32_bf16 v[20:23], v[164:167], v[196:199], v[20:23]
	v_mfma_f32_16x16x32_bf16 v[16:19], v[172:175], v[196:199], v[16:19]
	v_mfma_f32_16x16x32_bf16 v[4:7], v[164:167], v[206:209], v[4:7]
	v_mfma_f32_16x16x32_bf16 v[0:3], v[172:175], v[206:209], v[0:3]
	v_mfma_f32_16x16x32_bf16 v[52:55], v[168:171], v[184:187], v[52:55]
	v_mfma_f32_16x16x32_bf16 v[48:51], v[176:179], v[184:187], v[48:51]
	v_mfma_f32_16x16x32_bf16 v[36:39], v[168:171], v[192:195], v[36:39]
	v_mfma_f32_16x16x32_bf16 v[32:35], v[176:179], v[192:195], v[32:35]
	v_mfma_f32_16x16x32_bf16 v[20:23], v[168:171], v[202:205], v[20:23]
	v_mfma_f32_16x16x32_bf16 v[16:19], v[176:179], v[202:205], v[16:19]
	v_mfma_f32_16x16x32_bf16 v[4:7], v[168:171], v[210:213], v[4:7]
	v_mfma_f32_16x16x32_bf16 v[0:3], v[176:179], v[210:213], v[0:3]
	s_setprio 0
	s_waitcnt vmcnt(4)
	s_barrier
	s_add_i32 s62, s62, 2
	s_add_u32 s22, s22, 0x100
	s_addc_u32 s23, s23, 0
	s_cmpk_gt_u32 s62, 0x7d
	s_cbranch_scc0 .LBB0_2063
	s_and_b64 vcc, exec, s[10:11]
	s_cbranch_vccz .LBB0_2066
	s_barrier
